# kernel-level de-serialisation: cooperative-groups grid.sync at entry removed (first XCD barrier is self-synchronising) and the grid barrier after the last layer skipped (on top of v19)
# speedup vs baseline: 1.0020x; 1.0020x over previous
; #define LAS __attribute__((address_space(3)))
; __global__ void __launch_bounds__(NT, 2) mega(Params p) {
;     extern __shared__ __attribute__((aligned(16))) unsigned char lds_raw[];
;     lptr lds = (lptr)lds_raw;
;     cg::grid_group grid = cg::this_grid();
;     int G = gridDim.x, c = blockIdx.x;
;     unsigned char* ws = p.ws;
;     volatile LAS unsigned* bst = (volatile LAS unsigned*)(lds + LDS_BYTES - 16);
;     if (threadIdx.x < 4) bst[threadIdx.x] = 0u;
;     __syncthreads();
;     const XcdBarrier xbar = xcd_barrier_post((unsigned*)(p.ws + WS_BAR), bst);
;     grid.sync();
;     ...
;     bf16_t* xn = (bf16_t*)(ws + WS_XN); bf16_t* proj = (bf16_t*)(ws + WS_PROJ); bf16_t* hid = proj; unsigned char* gates = (unsigned char*)(ws + WS_GATES);
;     bf16_t* ysb = (bf16_t*)(ws + WS_YS); float* mf = (float*)(ws + WS_PROJ); bf16_t* merged = (bf16_t*)(ws + WS_MERGED);
;     float* x = p.out;
;     const LAS float* rstl_c = (const LAS float*)(lds + 131072); LAS float* rstl = (LAS float*)(lds + 131072);
;     float* rsqA = (float*)(ws + WS_RSQ); float* rsqB = rsqA + NTOK * 16; float* rsqC = rsqB + NTOK * 16;
.LBB0_5:
	s_or_b64 exec, exec, s[4:5]
	v_lshrrev_b32_e32 v1, 20, v0
	v_lshrrev_b32_e32 v0, 10, v0
	v_or_b32_e32 v0, v0, v1
	s_movk_i32 s4, 0x3ff
	v_and_or_b32 v0, v0, s4, v216
	v_cmp_eq_u32_e32 vcc, 0, v0
	s_barrier
	s_and_saveexec_b64 s[4:5], vcc
.LBB0_15:
	s_or_b64 exec, exec, s[4:5]
	s_load_dwordx16 s[4:19], s[0:1], 0x0
	s_load_dwordx16 s[72:87], s[0:1], 0xc0
	v_mov_b32_e32 v1, 0
	v_mbcnt_lo_u32_b32 v0, -1, 0
	v_mov_b32_e32 v217, 1
	s_waitcnt lgkmcnt(0)
	v_writelane_b32 v251, s4, 0
	v_mov_b32_e32 v218, 0x358637bd
	v_mov_b32_e32 v219, 0x3ecc95a3
	v_writelane_b32 v251, s5, 1
	v_writelane_b32 v251, s6, 2
	v_writelane_b32 v251, s7, 3
	v_writelane_b32 v251, s8, 4
	v_writelane_b32 v251, s9, 5
	v_writelane_b32 v251, s10, 6
	v_writelane_b32 v251, s11, 7
	v_writelane_b32 v251, s12, 8
	v_writelane_b32 v251, s13, 9
	v_writelane_b32 v251, s14, 10
	v_writelane_b32 v251, s15, 11
	v_writelane_b32 v251, s16, 12
	v_writelane_b32 v251, s17, 13
	v_writelane_b32 v251, s18, 14
	v_writelane_b32 v251, s19, 15
	s_load_dwordx16 s[8:23], s[0:1], 0x40
	s_load_dwordx16 s[36:51], s[0:1], 0x80
	s_add_u32 s0, s92, 0x4000000
	s_addc_u32 s1, s93, 0
	s_add_u32 s68, s92, 0x6000000
	s_addc_u32 s69, s93, 0
	s_waitcnt lgkmcnt(0)
	v_writelane_b32 v251, s36, 16
	v_mov_b32_e32 v238, 6
	v_mbcnt_hi_u32_b32 v234, -1, v0
	v_writelane_b32 v251, s37, 17
	v_writelane_b32 v251, s38, 18
	v_writelane_b32 v251, s39, 19
	v_writelane_b32 v251, s40, 20
	v_writelane_b32 v251, s41, 21
	v_writelane_b32 v251, s42, 22
	v_writelane_b32 v251, s43, 23
	v_writelane_b32 v251, s44, 24
	v_writelane_b32 v251, s45, 25
	v_writelane_b32 v251, s46, 26
	v_writelane_b32 v251, s47, 27
	v_writelane_b32 v251, s48, 28
	v_writelane_b32 v251, s49, 29
	v_writelane_b32 v251, s50, 30
	v_writelane_b32 v251, s51, 31
	v_writelane_b32 v251, s0, 32
	v_mov_b64_e32 v[184:185], 0x57f
	v_mov_b64_e32 v[186:187], 0x580
	v_writelane_b32 v251, s1, 33
	s_add_u32 s0, s92, 0xf900000
	s_addc_u32 s1, s93, 0
	v_writelane_b32 v251, s0, 34
	v_mov_b64_e32 v[188:189], 0x100
	v_mov_b64_e32 v[190:191], 0xff
	v_writelane_b32 v251, s1, 35
	s_add_u32 s0, s92, 0x17900000
	s_addc_u32 s1, s93, 0
	v_writelane_b32 v251, s0, 36
	v_mov_b64_e32 v[192:193], 0x8ff
	v_mov_b64_e32 v[194:195], 0x900
	v_writelane_b32 v251, s1, 37
	s_add_u32 s0, s92, 0xa000000
	s_addc_u32 s1, s93, 0
	v_writelane_b32 v251, s0, 38
	v_mov_b32_e32 v196, 0x3f317218
	v_mov_b32_e32 v235, 0x7f800000
	v_writelane_b32 v251, s1, 39
	s_add_u32 s0, s92, 0x1e981000
	s_addc_u32 s1, s93, 0
	v_writelane_b32 v251, s0, 40
	v_mov_b32_e32 v236, 0x7fc00000
	v_mov_b32_e32 v237, 0xff800000
	v_writelane_b32 v251, s1, 41
	s_add_u32 s0, s92, 0x1ea81000
	s_addc_u32 s1, s93, 0
	v_writelane_b32 v251, s0, 42
	v_mov_b32_e32 v241, 0x1100
	v_mov_b32_e32 v239, 0x900
	v_writelane_b32 v251, s1, 43
	s_add_u32 s0, s92, 0x1eb81000
	s_addc_u32 s1, s93, 0
	v_writelane_b32 v251, s0, 44
	s_lshl_b32 s6, s94, 3
	v_mov_b32_e32 v240, 0x2640
	v_writelane_b32 v251, s1, 45
	s_lshl_b32 s1, s71, 3
	s_add_u32 s4, s92, 0x3a04000
	v_writelane_b32 v251, s1, 46
	s_addc_u32 s5, s93, 0
	v_writelane_b32 v251, s4, 47
	s_mul_i32 s0, s95, s94
	s_mul_i32 s95, s0, s25
	v_writelane_b32 v251, s5, 48
	s_add_u32 s4, s92, 0x3a00000
	s_addc_u32 s5, s93, 0
	v_writelane_b32 v251, s4, 49
	v_mov_b32_e32 v244, 0xf149f2ca
	v_mov_b32_e32 v245, 0x4e6e6b28
	v_writelane_b32 v251, s5, 50
	s_add_u32 s4, s92, 0x3980000
	s_addc_u32 s5, s93, 0
	v_writelane_b32 v251, s4, 51
	v_mov_b32_e32 v246, 0xff61b1e6
	v_mov_b32_e32 v247, 0x3b808081
	v_writelane_b32 v251, s5, 52
	s_add_u32 s4, s92, 0x3900000
	s_addc_u32 s5, s93, 0
	v_writelane_b32 v251, s4, 53
	s_movk_i32 s91, 0x100
	s_movk_i32 s70, 0x2640
	v_writelane_b32 v251, s5, 54
	s_add_u32 s4, s92, 0xb00000
	s_addc_u32 s5, s93, 0
	v_writelane_b32 v251, s4, 55
	s_mov_b32 s90, 0x5040100
	s_mov_b32 s40, 0
	v_writelane_b32 v251, s5, 56
	s_add_u32 s4, s92, 0x1080000
	s_addc_u32 s5, s93, 0
	v_writelane_b32 v251, s4, 57
	s_add_u32 s0, s92, 0x1ec81200
	s_addc_u32 s1, s93, 0
	v_writelane_b32 v251, s5, 58
	v_writelane_b32 v251, s0, 59
	s_mov_b32 s35, 0
	s_mov_b64 s[64:65], s[92:93]
	v_writelane_b32 v251, s1, 60
	s_add_u32 s0, s92, 0x1ec81400
	s_addc_u32 s1, s93, 0
	v_writelane_b32 v251, s0, 61
	s_barrier
	s_nop 0
	v_writelane_b32 v251, s1, 62
	s_add_u32 s0, s92, 0x1ec81500
	s_addc_u32 s1, s93, 0
	v_writelane_b32 v251, s0, 63
	s_nop 1
	v_writelane_b32 v252, s1, 0
	s_add_u32 s0, s92, 0x1ec81600
	s_addc_u32 s1, s93, 0
	v_writelane_b32 v252, s0, 1
	s_nop 1
	v_writelane_b32 v252, s1, 2
	s_add_u32 s0, s92, 0x1ec81700
	s_addc_u32 s1, s93, 0
	v_writelane_b32 v252, s0, 3
	s_nop 1
	v_writelane_b32 v252, s1, 4
	s_add_u32 s0, s92, 0x1ec81800
	s_addc_u32 s1, s93, 0
	v_writelane_b32 v252, s0, 5
	s_nop 1
	v_writelane_b32 v252, s1, 6
	s_add_u32 s0, s92, 0x1ec81900
	s_addc_u32 s1, s93, 0
	v_writelane_b32 v252, s0, 7
	s_nop 1
	v_writelane_b32 v252, s1, 8
	s_add_u32 s0, s92, 0x1ec81a00
	s_addc_u32 s1, s93, 0
	v_writelane_b32 v252, s0, 9
	s_nop 1
	v_writelane_b32 v252, s1, 10
	s_add_u32 s0, s92, 0x1ec81b00
	s_addc_u32 s1, s93, 0
	v_writelane_b32 v252, s0, 11
	s_nop 1
	v_writelane_b32 v252, s1, 12
	s_add_u32 s0, s92, 0x1ec81c00
	s_addc_u32 s1, s93, 0
	v_writelane_b32 v252, s0, 13
	s_nop 1
	v_writelane_b32 v252, s1, 14
	s_add_u32 s0, s92, 0x1ec81d00
	s_addc_u32 s1, s93, 0
	v_writelane_b32 v252, s0, 15
	s_nop 1
	v_writelane_b32 v252, s1, 16
	s_add_u32 s0, s92, 0x1ec81e00
	s_addc_u32 s1, s93, 0
	v_writelane_b32 v252, s0, 17
	s_nop 1
	v_writelane_b32 v252, s1, 18
	s_add_u32 s0, s92, 0x1ec81f00
	s_addc_u32 s1, s93, 0
	v_writelane_b32 v252, s0, 19
	s_nop 1
	v_writelane_b32 v252, s1, 20
	s_add_u32 s0, s92, 0x1ec82000
	s_addc_u32 s1, s93, 0
; #define LAS __attribute__((address_space(3)))
; __device__ __forceinline__ unsigned xb_ld(unsigned* p)              { return __hip_atomic_load(p, __ATOMIC_RELAXED, __HIP_MEMORY_SCOPE_AGENT); }
; __device__ __forceinline__ unsigned xb_add(unsigned* p, unsigned v) { return __hip_atomic_fetch_add(p, v, __ATOMIC_RELAXED, __HIP_MEMORY_SCOPE_AGENT); }
; __device__ __forceinline__ unsigned xb_xcc_id() { return (unsigned)__builtin_amdgcn_s_getreg((3 << 11) | 20) & 0xFu; }
; __device__ __forceinline__ XcdBarrier xcd_barrier_post(unsigned* bar, volatile LAS unsigned* st) {
;     XcdBarrier b; b.bar = bar; b.x = xb_xcc_id(); b.st = st;
;     if (threadIdx.x == 0) (void)xb_add(&bar[XB_XCNT(b.x)], 1u);
;     return b;
; }
; __device__ __forceinline__ void xcd_barrier_complete(unsigned* bar, unsigned x, unsigned& nloc, unsigned& nx) {
;     const unsigned G = gridDim.x * gridDim.y * gridDim.z;
;     unsigned sum, cnt, mine, sp = 0u;
;     for (;;) {
;         sum = 0u; cnt = 0u; mine = 0u;
; #pragma unroll
;         for (unsigned j = 0; j < 16; ++j) { const unsigned c = xb_ld(&bar[XB_XCNT(j)]); sum += c; cnt += (c > 0u) ? 1u : 0u; mine = (j == x) ? c : mine; }
;         if (sum == G) break;
;         __builtin_amdgcn_s_sleep(1);
;         if ((++sp & 255u) == 0u) { if (xb_ld(&bar[XB_TMO])) break; if (sp > XB_SPIN_CAP) { atomicAdd(&bar[XB_TMO], 1u); break; } }
;     }
;     nloc = mine > 0u ? mine : 1u; nx = cnt > 0u ? cnt : 1u;
; __global__ void __launch_bounds__(NT, 2) mega(Params p) {
;     ...
;     bf16_t* xn = (bf16_t*)(ws + WS_XN); bf16_t* proj = (bf16_t*)(ws + WS_PROJ); bf16_t* hid = proj; unsigned char* gates = (unsigned char*)(ws + WS_GATES);
;     bf16_t* ysb = (bf16_t*)(ws + WS_YS); float* mf = (float*)(ws + WS_PROJ); bf16_t* merged = (bf16_t*)(ws + WS_MERGED);
;     float* x = p.out;
;     const LAS float* rstl_c = (const LAS float*)(lds + 131072); LAS float* rstl = (LAS float*)(lds + 131072);
;     float* rsqA = (float*)(ws + WS_RSQ); float* rsqB = rsqA + NTOK * 16; float* rsqC = rsqB + NTOK * 16;
	v_writelane_b32 v252, s0, 21
	s_nop 1
	v_writelane_b32 v252, s1, 22
	s_add_u32 s0, s92, 0x1ec82100
	s_addc_u32 s1, s93, 0
	v_writelane_b32 v252, s0, 23
	s_nop 1
	v_writelane_b32 v252, s1, 24
	s_add_u32 s0, s92, 0x1ec82200
	s_addc_u32 s1, s93, 0
	v_writelane_b32 v252, s0, 25
	s_nop 1
	v_writelane_b32 v252, s1, 26
	s_add_u32 s0, s92, 0x1ec82300
	s_addc_u32 s1, s93, 0
	v_writelane_b32 v252, s0, 27
	s_cmp_eq_u32 s24, 15
	s_nop 0
	v_writelane_b32 v252, s1, 28
	s_cselect_b64 s[0:1], -1, 0
	v_writelane_b32 v252, s0, 29
	s_cmp_eq_u32 s24, 14
	s_nop 0
	v_writelane_b32 v252, s1, 30
	s_cselect_b64 s[0:1], -1, 0
	v_writelane_b32 v252, s0, 31
	s_cmp_eq_u32 s24, 13
	s_nop 0
	v_writelane_b32 v252, s1, 32
	s_cselect_b64 s[0:1], -1, 0
	v_writelane_b32 v252, s0, 33
	s_cmp_eq_u32 s24, 12
	s_nop 0
	v_writelane_b32 v252, s1, 34
	s_cselect_b64 s[0:1], -1, 0
	v_writelane_b32 v252, s0, 35
	s_cmp_eq_u32 s24, 11
	s_nop 0
	v_writelane_b32 v252, s1, 36
	s_cselect_b64 s[0:1], -1, 0
	v_writelane_b32 v252, s0, 37
	s_cmp_eq_u32 s24, 10
	s_nop 0
	v_writelane_b32 v252, s1, 38
	s_cselect_b64 s[0:1], -1, 0
	v_writelane_b32 v252, s0, 39
	s_cmp_eq_u32 s24, 9
	s_nop 0
	v_writelane_b32 v252, s1, 40
	s_cselect_b64 s[0:1], -1, 0
	v_writelane_b32 v252, s0, 41
	s_cmp_eq_u32 s24, 8
	s_nop 0
	v_writelane_b32 v252, s1, 42
	s_cselect_b64 s[0:1], -1, 0
	v_writelane_b32 v252, s0, 43
	s_cmp_eq_u32 s24, 7
	s_nop 0
	v_writelane_b32 v252, s1, 44
	s_cselect_b64 s[0:1], -1, 0
	v_writelane_b32 v252, s0, 45
	s_cmp_eq_u32 s24, 6
	s_nop 0
	v_writelane_b32 v252, s1, 46
	s_cselect_b64 s[0:1], -1, 0
	v_writelane_b32 v252, s0, 47
	s_cmp_eq_u32 s24, 5
	s_nop 0
	v_writelane_b32 v252, s1, 48
	s_cselect_b64 s[0:1], -1, 0
	v_writelane_b32 v252, s0, 49
	s_cmp_eq_u32 s24, 4
	s_nop 0
	v_writelane_b32 v252, s1, 50
	s_cselect_b64 s[0:1], -1, 0
	v_writelane_b32 v252, s0, 51
	s_cmp_eq_u32 s24, 3
	s_nop 0
	v_writelane_b32 v252, s1, 52
	s_cselect_b64 s[0:1], -1, 0
	v_writelane_b32 v252, s0, 53
	s_cmp_eq_u32 s24, 2
	s_nop 0
	v_writelane_b32 v252, s1, 54
	s_cselect_b64 s[0:1], -1, 0
	v_writelane_b32 v252, s0, 55
	s_cmp_eq_u32 s24, 1
	s_nop 0
	v_writelane_b32 v252, s1, 56
	s_cselect_b64 s[0:1], -1, 0
	v_writelane_b32 v252, s0, 57
	s_cmp_eq_u32 s24, 0
	s_nop 0
	v_writelane_b32 v252, s1, 58
	s_cselect_b64 s[0:1], -1, 0
	v_writelane_b32 v252, s0, 59
	s_nop 1
	v_writelane_b32 v252, s1, 60
	s_lshl_b32 s0, s24, 8
	s_add_u32 s0, s2, s0
	s_addc_u32 s1, s3, 0
	s_add_u32 s2, s0, 0x1400
	s_addc_u32 s3, s1, 0
	v_writelane_b32 v252, s2, 61
	s_add_u32 s0, s0, 0x2400
	s_addc_u32 s1, s1, 0
	v_writelane_b32 v252, s3, 62
	v_writelane_b32 v252, s0, 63
	s_nop 1
	v_writelane_b32 v253, s1, 0
	s_add_u32 s0, s92, 0x1ec84400
	s_addc_u32 s1, s93, 0
	v_writelane_b32 v253, s0, 1
	s_nop 1
	v_writelane_b32 v253, s1, 2
	s_add_u32 s0, s92, 0x1ec84500
	s_addc_u32 s1, s93, 0
	v_writelane_b32 v253, s0, 3
	s_nop 1
	v_writelane_b32 v253, s1, 4
	s_lshl_b32 s0, s71, 9
	v_writelane_b32 v253, s0, 5
	s_lshl_b32 s0, s94, 9
	v_writelane_b32 v253, s0, 6
	s_add_u32 s0, s92, 0x1b900000
	s_addc_u32 s1, s93, 0
	v_writelane_b32 v253, s0, 7
	s_nop 1
	v_writelane_b32 v253, s1, 8
	s_add_u32 s0, s92, 0x1d900000
	s_addc_u32 s1, s93, 0
	v_writelane_b32 v253, s0, 9
	s_nop 1
	v_writelane_b32 v253, s1, 10
	s_add_u32 s0, s92, 0x1d941000
	s_addc_u32 s1, s93, 0
	v_writelane_b32 v253, s0, 11
	s_nop 1
	v_writelane_b32 v253, s1, 12
	s_add_u32 s0, s92, 0x1d901000
	v_writelane_b32 v253, s0, 13
	s_addc_u32 s0, s93, 0
	s_add_u32 s4, s92, 0x1d981000
	s_addc_u32 s5, s93, 0
	v_writelane_b32 v253, s0, 14
	s_add_u32 s0, s92, 0x2680000
	s_addc_u32 s1, s93, 0
	v_writelane_b32 v253, s0, 15
	s_nop 1
	v_writelane_b32 v253, s1, 16
	s_add_u32 s0, s92, 0x2280000
	s_addc_u32 s1, s93, 0
	v_writelane_b32 v253, s0, 17
	s_nop 1
	v_writelane_b32 v253, s1, 18
	s_add_u32 s0, s92, 0x3380000
	s_addc_u32 s1, s93, 0
	v_writelane_b32 v253, s0, 19
	s_nop 1
	v_writelane_b32 v253, s1, 20
	s_add_u32 s0, s92, 0x2880000
	s_addc_u32 s1, s93, 0
	v_writelane_b32 v253, s0, 21
	s_ashr_i32 s7, s6, 31
	s_nop 0
	v_writelane_b32 v253, s1, 22
	s_lshl_b32 s0, s71, 11
	v_writelane_b32 v253, s0, 23
	s_lshl_b32 s0, s94, 11
	v_writelane_b32 v253, s0, 24
	s_lshl_b64 s[0:1], s[6:7], 6
	v_writelane_b32 v253, s0, 25
	s_nop 1
	v_writelane_b32 v253, s1, 26
	s_lshl_b64 s[0:1], s[6:7], 11
	v_writelane_b32 v253, s0, 27
	s_nop 1
	v_writelane_b32 v253, s1, 28
	s_mov_b32 s0, s6
	v_writelane_b32 v253, s0, 29
	s_nop 1
	v_writelane_b32 v253, s1, 30
	s_lshl_b64 s[0:1], s[6:7], 12
	v_writelane_b32 v253, s0, 31
	s_mov_b64 s[6:7], 0x80
	s_nop 0
	v_writelane_b32 v253, s1, 32
	s_add_u32 s0, s92, 0x17900440
	s_addc_u32 s1, s93, 0
	v_writelane_b32 v253, s0, 33
	s_add_i32 s33, 0, 0x1bc00
	s_nop 0
	v_writelane_b32 v253, s1, 34
	s_add_i32 s0, 0, 0x23ff0
	v_writelane_b32 v253, s0, 35
	s_add_i32 s0, 0, 0x23ff4
	v_writelane_b32 v253, s0, 36
	s_add_i32 s0, 0, 0x20000
	v_writelane_b32 v253, s0, 37
	s_add_i32 s0, 0, 0x18c00
	v_writelane_b32 v253, s0, 38
	s_add_i32 s0, 0, 0x1d000
	v_writelane_b32 v253, s0, 39
	s_add_i32 s0, 0, 0x23ff8
	v_writelane_b32 v253, s0, 40
	s_add_i32 s0, 0, 0x11500
	v_writelane_b32 v253, s0, 41
	s_add_i32 s0, 0, 0x15900
	v_writelane_b32 v253, s0, 42
	s_add_i32 s0, 0, 0x1e900
	v_writelane_b32 v253, s0, 43
	s_add_i32 s0, 0, 0x20d00
	v_writelane_b32 v253, s0, 44
	s_add_i32 s0, 0, 0x13000
	v_writelane_b32 v253, s0, 45
	s_add_i32 s0, 0, 0x17800
	v_writelane_b32 v253, s0, 46
	v_writelane_b32 v253, s96, 47
	s_nop 1
	v_writelane_b32 v253, s97, 48
	v_writelane_b32 v253, s72, 49
	s_nop 1
	v_writelane_b32 v253, s73, 50
	v_writelane_b32 v253, s74, 51
	v_writelane_b32 v253, s75, 52
	v_writelane_b32 v253, s76, 53
	v_writelane_b32 v253, s77, 54
	v_writelane_b32 v253, s78, 55
	v_writelane_b32 v253, s79, 56
	v_writelane_b32 v253, s80, 57
	v_writelane_b32 v253, s81, 58
	v_writelane_b32 v253, s82, 59
	v_writelane_b32 v253, s83, 60
	v_writelane_b32 v254, s87, 0
	v_writelane_b32 v253, s84, 61
	v_writelane_b32 v254, s68, 1
	v_writelane_b32 v253, s85, 62
	v_writelane_b32 v253, s86, 63
	v_writelane_b32 v254, s69, 2
	v_writelane_b32 v254, s95, 3
	s_branch .LBB0_18

;     __device__ void init(int G_, int c_) { so.init(NTOK, DM, G_, c_); }
; #define OPQ() asm volatile("" : "+s"(G), "+s"(c), "+s"(l), "+s"(ws))
; __device__ __forceinline__ void xcd_barrier(const XcdBarrier& b) {
;     asm volatile("s_waitcnt vmcnt(0)" ::: "memory");
;     __syncthreads();
;     if (threadIdx.x == 0) {
; __global__ void __launch_bounds__(NT, 2) mega(Params p) {
;     ...
;         { const bool lastl = (l == NLAYER - 1); pg8::Gemm g{hid, (const bf16_t*)(ws + WS_W2OUT), FF, FF}; pg8::StaticOrder S; S.init(NTOK, DM, G, c);
;           pg8::EpiResid E{x, x, 0.5f, lastl ? (bf16_t*)nullptr : xn, p.in[I_F1N] + (lastl ? l : l + 1) * DM, rsqA}; pg8::gemm_phase(lds, g, S, E); }
;         xcd_barrier(xbar); OPQ();
;     }
; }
.LBB0_2473:
	v_readlane_b32 s0, v254, 4
	s_nop 3
	s_cmp_eq_u32 s0, 3
	s_cbranch_scc1 .LBB0_2524
	s_waitcnt vmcnt(0)
	s_waitcnt lgkmcnt(0)
	s_barrier
	s_and_saveexec_b64 s[0:1], s[96:97]
	v_readlane_b32 s40, v254, 4
	s_cbranch_execnz .LBB0_2474
	s_getpc_b64 s[98:99]
